# two-level hand-off publishes (hand1 after w_o, handA after P9a): only the last workgroup of each XCD writes back L2 and publishes for the XCD, instead of one buffer_wbl2 per workgroup
# speedup vs baseline: 1.0452x; 1.0245x over previous
; #define HAND_PUBLISH(p) do { asm volatile("s_waitcnt vmcnt(0)" ::: "memory"); __syncthreads(); \
;                 if (otid() == 0) { __builtin_amdgcn_fence(__ATOMIC_RELEASE, "agent"); asm volatile("s_waitcnt vmcnt(0)" ::: "memory"); (void)xb_add((p), 1u); } } while (0)
; __global__ void __launch_bounds__(512, 2) mega(Params P) {
;     ...
;             run_gemm_sub(g_wave, lds, UP(U_MIX), WOl, MP, 1024, 1024, 0, G, bid, e);
;             HAND_PUBLISH(hand1);
;             if (bid < 16) {
.LBB0_1146:
	v_readlane_b32 s6, v254, 56
	s_lshl_b32 s10, s6, 6
	s_mov_b32 s1, s11
	v_readlane_b32 s7, v254, 57
	v_writelane_b32 v254, s0, 16
	s_lshl_b64 s[2:3], s[10:11], 2
	s_waitcnt vmcnt(0)
	s_waitcnt lgkmcnt(0)
	v_writelane_b32 v254, s1, 17
	s_add_u32 s0, s50, s2
	v_writelane_b32 v255, s2, 1
	s_addc_u32 s1, s51, s3
	s_add_u32 s10, s0, 0x39d0
	v_readlane_b32 s0, v253, 32
	s_barrier
	v_mbcnt_lo_u32_b32 v0, -1, 0
	v_mbcnt_hi_u32_b32 v0, -1, v0
	s_addc_u32 s11, s1, 0
	s_lshl_b32 s0, s0, 6
	v_sub_u32_e32 v0, 0, v0
	v_writelane_b32 v255, s3, 2
	v_cmp_eq_u32_e32 vcc, s0, v0
	s_and_saveexec_b64 s[0:1], vcc
	s_cbranch_execz .LBB0_1149
	s_getreg_b32 s12, hwreg(HW_REG_XCC_ID, 0, 4)
	s_and_b32 s12, s12, 15
	s_lshl_b32 s12, s12, 2
	v_mov_b32_e32 v72, 0x23fc8
	ds_read_b32 v73, v72
	v_mov_b32_e32 v74, s12
	v_mov_b32_e32 v75, 1
	global_atomic_add v76, v74, v75, s[10:11] offset:68 sc0
	s_waitcnt vmcnt(0) lgkmcnt(0)
	v_add_u32_e32 v76, 1, v76
	v_cmp_eq_u32_e32 vcc, v76, v73
	s_and_b64 vcc, exec, vcc
	s_cbranch_vccz .Lpub_h1_skip
	buffer_wbl2 sc1
	s_waitcnt vmcnt(0)
	global_atomic_add v225, v73, s[10:11] offset:64
.Lpub_h1_skip:
.LBB0_1149:
	s_or_b64 exec, exec, s[0:1]
	s_add_u32 s0, s26, 0x890000
	v_writelane_b32 v254, s0, 42
	s_addc_u32 s0, s27, 0
	v_writelane_b32 v254, s0, 44
	s_mov_b64 s[0:1], -1
	v_readlane_b32 s84, v254, 19
	s_cmp_gt_i32 s14, 15
	s_mul_i32 s71, s6, 0x8400
	s_mul_i32 s15, s6, 0x2c00
	v_readlane_b32 s86, v254, 21
	v_readlane_b32 s87, v254, 22
	v_readlane_b32 s88, v254, 23
	v_readlane_b32 s89, v254, 24
	v_readlane_b32 s90, v254, 25
	v_readlane_b32 s91, v254, 26
	v_readlane_b32 s52, v254, 46
	v_readlane_b32 s85, v254, 20
	s_cbranch_scc0 .LBB0_1280
	v_readlane_b32 s0, v253, 32
	v_mbcnt_lo_u32_b32 v0, -1, 0
	v_mbcnt_hi_u32_b32 v0, -1, v0
	s_lshl_b32 s0, s0, 6
	v_sub_u32_e32 v0, 0, v0
	v_cmp_eq_u32_e32 vcc, s0, v0
	s_and_saveexec_b64 s[0:1], vcc
	s_cbranch_execz .LBB0_1160
	s_mov_b32 s4, 0x400001
	s_branch .LBB0_1153

; #define otid() otid_w(g_wave)
; DI unsigned xb_ld(unsigned* p)              { return __hip_atomic_load(p, __ATOMIC_RELAXED, __HIP_MEMORY_SCOPE_AGENT); }
; DI unsigned xb_add(unsigned* p, unsigned v) { return __hip_atomic_fetch_add(p, v, __ATOMIC_RELAXED, __HIP_MEMORY_SCOPE_AGENT); }
; __global__ void __launch_bounds__(512, 2) mega(Params P) {
;     ...
;             asm volatile("s_waitcnt vmcnt(0)" ::: "memory");
;             __syncthreads();
;             if (otid() == 0) { __builtin_amdgcn_fence(__ATOMIC_RELEASE, "agent"); asm volatile("s_waitcnt vmcnt(0)" ::: "memory"); (void)xb_add(WSP(unsigned, WS_CTL) + 3700 + 64 * l + 48, 1u); }
;     ...
;             if (bid >= 16) {
;                 unsigned* handA = WSP(unsigned, WS_CTL) + 3700 + 64 * l + 48;
;                 if (otid() == 0) { unsigned sp_ = 0u; while (xb_ld(handA) < (unsigned)G) { __builtin_amdgcn_s_sleep(2); if (++sp_ > (1u << 22)) break; }
.LBB0_1660:
	s_mov_b32 s2, s21
	s_waitcnt vmcnt(0)
	s_waitcnt vmcnt(0) lgkmcnt(0)
	s_barrier
	v_mbcnt_lo_u32_b32 v0, -1, 0
	v_mbcnt_hi_u32_b32 v0, -1, v0
	s_lshl_b32 s2, s2, 6
	v_sub_u32_e32 v0, 0, v0
	v_cmp_eq_u32_e32 vcc, s2, v0
	s_and_saveexec_b64 s[2:3], vcc
	s_cbranch_execz .LBB0_1663
	v_readlane_b32 s6, v255, 1
	v_readlane_b32 s7, v255, 2
	s_add_u32 s6, s10, s6
	s_addc_u32 s7, s11, s7
	s_getreg_b32 s12, hwreg(HW_REG_XCC_ID, 0, 4)
	s_and_b32 s12, s12, 15
	s_lshl_b32 s12, s12, 2
	s_add_i32 s12, s12, 0x3000
	v_mov_b32_e32 v72, 0x23fc8
	ds_read_b32 v73, v72
	v_mov_b32_e32 v74, s12
	v_mov_b32_e32 v75, 1
	global_atomic_add v76, v74, v75, s[6:7] offset:2708 sc0
	s_waitcnt vmcnt(0) lgkmcnt(0)
	v_add_u32_e32 v76, 1, v76
	v_cmp_eq_u32_e32 vcc, v76, v73
	s_and_b64 vcc, exec, vcc
	s_cbranch_vccz .Lpub_hA_skip
	buffer_wbl2 sc1
	s_waitcnt vmcnt(0)
	v_mov_b32_e32 v1, 0x3000
	global_atomic_add v1, v73, s[6:7] offset:2704
.Lpub_hA_skip:
.LBB0_1663:
	s_or_b64 exec, exec, s[2:3]
	s_mov_b32 s6, s21
	s_mov_b32 s38, s97
	s_mov_b64 s[14:15], s[90:91]
	v_readlane_b32 s2, v255, 1
	v_mbcnt_lo_u32_b32 v0, -1, 0
	v_mbcnt_hi_u32_b32 v0, -1, v0
	v_readlane_b32 s3, v255, 2
	s_add_u32 s2, s14, s2
	s_addc_u32 s3, s15, s3
	s_add_u32 s24, s2, 0x39d0
	s_addc_u32 s25, s3, 0
	s_mov_b64 s[84:85], s[88:89]
	s_cmp_lt_i32 s38, 16
	s_cbranch_scc1 .LBB0_1673
	s_mov_b32 s2, s21
	v_mbcnt_lo_u32_b32 v1, -1, 0
	v_mbcnt_hi_u32_b32 v1, -1, v1
	s_lshl_b32 s2, s2, 6
	v_sub_u32_e32 v1, 0, v1
	v_cmp_eq_u32_e32 vcc, s2, v1
	s_and_saveexec_b64 s[2:3], vcc
	s_cbranch_execz .LBB0_1689
	s_mov_b32 s7, 0x400001
	s_branch .LBB0_1667
